# v20 + grid barrier: non-leader WGs poll the global TOPGEN word instead of the per-XCD XGEN word (one fewer atomic hop per barrier)
# speedup vs baseline: 1.0067x; 1.0058x over previous
; __device__ __forceinline__ unsigned xb_ld(unsigned* p)              { return __hip_atomic_load(p, __ATOMIC_RELAXED, __HIP_MEMORY_SCOPE_AGENT); }
; __device__ __forceinline__ unsigned xb_add(unsigned* p, unsigned v) { return __hip_atomic_fetch_add(p, v, __ATOMIC_RELAXED, __HIP_MEMORY_SCOPE_AGENT); }
; #define XB_SPIN(cond, bar) do { unsigned _sp = 0; while (cond) { __builtin_amdgcn_s_sleep(1); \
;     if ((++_sp & 255u) == 0u) { if (xb_ld(&(bar)[XB_TMO])) break; if (_sp > XB_SPIN_CAP) { atomicAdd(&(bar)[XB_TMO], 1u); break; } } } } while (0)
; __device__ __forceinline__ void xcd_barrier(const XcdBarrier& b, const int wid) {
;     ...
;         const unsigned old = xb_add(&bar[XB_XSUB(b.x)], 1u);
;         const unsigned gen = old / nloc;
;         if (old + 1u == (gen + 1u) * nloc) {
;             __builtin_amdgcn_fence(__ATOMIC_RELEASE, "agent");
;             asm volatile("s_waitcnt vmcnt(0)" ::: "memory");
;             const unsigned og = xb_add(&bar[XB_TOP], 1u);
;             const unsigned tg = og / nx;
;             if (og + 1u == (tg + 1u) * nx) xb_add(&bar[XB_TOPGEN], 1u);
;             else XB_SPIN(xb_ld(&bar[XB_TOPGEN]) == tg, bar);
;             __builtin_amdgcn_fence(__ATOMIC_ACQUIRE, "agent");
;             xb_add(&bar[XB_XGEN(b.x)], 1u);
;             asm volatile("s_waitcnt vmcnt(0)" ::: "memory");
;         } else {
;             XB_SPIN(xb_ld(&bar[XB_XGEN(b.x)]) == gen, bar);
.LBB0_327:
	s_or_b64 exec, exec, s[12:13]
	v_cvt_f32_u32_e32 v4, v2
	s_waitcnt vmcnt(0)
	v_readfirstlane_b32 s3, v3
	v_sub_u32_e32 v3, 0, v2
	v_rcp_iflag_f32_e32 v4, v4
	v_add_u32_e32 v5, s3, v1
	v_mul_f32_e32 v4, 0x4f7ffffe, v4
	v_cvt_u32_f32_e32 v4, v4
	v_mul_lo_u32 v1, v3, v4
	v_mul_hi_u32 v1, v4, v1
	v_add_u32_e32 v1, v4, v1
	v_mul_hi_u32 v1, v5, v1
	v_mul_lo_u32 v3, v1, v2
	v_sub_u32_e32 v3, v5, v3
	v_add_u32_e32 v4, 1, v1
	v_cmp_ge_u32_e32 vcc, v3, v2
	s_nop 1
	v_cndmask_b32_e32 v1, v1, v4, vcc
	v_sub_u32_e32 v4, v3, v2
	v_cndmask_b32_e32 v3, v3, v4, vcc
	v_add_u32_e32 v4, 1, v1
	v_cmp_ge_u32_e32 vcc, v3, v2
	v_add_u32_e32 v3, 1, v5
	s_nop 0
	v_cndmask_b32_e32 v1, v1, v4, vcc
	v_mul_lo_u32 v4, v2, v1
	v_add_u32_e32 v2, v4, v2
	v_cmp_ne_u32_e32 vcc, v3, v2
	s_and_saveexec_b64 s[10:11], vcc
	s_xor_b64 s[10:11], exec, s[10:11]
	s_cbranch_execz .LBB0_341
	s_waitcnt lgkmcnt(0)
	v_mov_b32_e32 v0, 0x7000
	global_load_dword v0, v0, s[46:47] offset:1280 sc1
	s_add_u32 s16, s46, 0x7500
	s_addc_u32 s17, s47, 0
	s_waitcnt vmcnt(0)
	v_cmp_eq_u32_e32 vcc, v0, v1
	s_and_saveexec_b64 s[12:13], vcc
	s_cbranch_execz .LBB0_340
	s_add_u32 s14, s46, 0x4200
	s_addc_u32 s15, s47, 0
	s_mov_b32 s3, 1
	s_mov_b64 s[18:19], 0
	v_mov_b32_e32 v0, 0
	s_branch .LBB0_331

; __device__ __forceinline__ unsigned xb_ld(unsigned* p)              { return __hip_atomic_load(p, __ATOMIC_RELAXED, __HIP_MEMORY_SCOPE_AGENT); }
; __device__ __forceinline__ unsigned xb_add(unsigned* p, unsigned v) { return __hip_atomic_fetch_add(p, v, __ATOMIC_RELAXED, __HIP_MEMORY_SCOPE_AGENT); }
; #define XB_SPIN(cond, bar) do { unsigned _sp = 0; while (cond) { __builtin_amdgcn_s_sleep(1); \
;     if ((++_sp & 255u) == 0u) { if (xb_ld(&(bar)[XB_TMO])) break; if (_sp > XB_SPIN_CAP) { atomicAdd(&(bar)[XB_TMO], 1u); break; } } } } while (0)
; __device__ __forceinline__ void xcd_barrier(const XcdBarrier& b, const int wid) {
;     ...
;         const unsigned old = xb_add(&bar[XB_XSUB(b.x)], 1u);
;         const unsigned gen = old / nloc;
;         if (old + 1u == (gen + 1u) * nloc) {
;             __builtin_amdgcn_fence(__ATOMIC_RELEASE, "agent");
;             asm volatile("s_waitcnt vmcnt(0)" ::: "memory");
;             const unsigned og = xb_add(&bar[XB_TOP], 1u);
;             const unsigned tg = og / nx;
;             if (og + 1u == (tg + 1u) * nx) xb_add(&bar[XB_TOPGEN], 1u);
;             else XB_SPIN(xb_ld(&bar[XB_TOPGEN]) == tg, bar);
;             __builtin_amdgcn_fence(__ATOMIC_ACQUIRE, "agent");
;             xb_add(&bar[XB_XGEN(b.x)], 1u);
;             asm volatile("s_waitcnt vmcnt(0)" ::: "memory");
;         } else {
;             XB_SPIN(xb_ld(&bar[XB_XGEN(b.x)]) == gen, bar);
.LBB0_2184:
	s_or_b64 exec, exec, s[14:15]
	v_cvt_f32_u32_e32 v4, v2
	s_waitcnt vmcnt(0)
	v_readfirstlane_b32 s3, v3
	v_sub_u32_e32 v3, 0, v2
	v_rcp_iflag_f32_e32 v4, v4
	v_add_u32_e32 v5, s3, v1
	v_mul_f32_e32 v4, 0x4f7ffffe, v4
	v_cvt_u32_f32_e32 v4, v4
	v_mul_lo_u32 v1, v3, v4
	v_mul_hi_u32 v1, v4, v1
	v_add_u32_e32 v1, v4, v1
	v_mul_hi_u32 v1, v5, v1
	v_mul_lo_u32 v3, v1, v2
	v_sub_u32_e32 v3, v5, v3
	v_add_u32_e32 v4, 1, v1
	v_cmp_ge_u32_e32 vcc, v3, v2
	s_nop 1
	v_cndmask_b32_e32 v1, v1, v4, vcc
	v_sub_u32_e32 v4, v3, v2
	v_cndmask_b32_e32 v3, v3, v4, vcc
	v_add_u32_e32 v4, 1, v1
	v_cmp_ge_u32_e32 vcc, v3, v2
	v_add_u32_e32 v3, 1, v5
	s_nop 0
	v_cndmask_b32_e32 v1, v1, v4, vcc
	v_mul_lo_u32 v4, v2, v1
	v_add_u32_e32 v2, v4, v2
	v_cmp_ne_u32_e32 vcc, v3, v2
	s_and_saveexec_b64 s[12:13], vcc
	s_xor_b64 s[12:13], exec, s[12:13]
	s_cbranch_execz .LBB0_2198
	s_waitcnt lgkmcnt(0)
	v_mov_b32_e32 v0, 0x7000
	global_load_dword v0, v0, s[46:47] offset:1280 sc1
	s_add_u32 s18, s46, 0x7500
	s_addc_u32 s19, s47, 0
	s_waitcnt vmcnt(0)
	v_cmp_eq_u32_e32 vcc, v0, v1
	s_and_saveexec_b64 s[14:15], vcc
	s_cbranch_execz .LBB0_2197
	s_add_u32 s16, s46, 0x4200
	s_addc_u32 s17, s47, 0
	s_mov_b32 s3, 1
	s_mov_b64 s[20:21], 0
	v_mov_b32_e32 v0, 0
	s_branch .LBB0_2188

; __device__ __forceinline__ unsigned xb_ld(unsigned* p)              { return __hip_atomic_load(p, __ATOMIC_RELAXED, __HIP_MEMORY_SCOPE_AGENT); }
; __device__ __forceinline__ unsigned xb_add(unsigned* p, unsigned v) { return __hip_atomic_fetch_add(p, v, __ATOMIC_RELAXED, __HIP_MEMORY_SCOPE_AGENT); }
; #define XB_SPIN(cond, bar) do { unsigned _sp = 0; while (cond) { __builtin_amdgcn_s_sleep(1); \
;     if ((++_sp & 255u) == 0u) { if (xb_ld(&(bar)[XB_TMO])) break; if (_sp > XB_SPIN_CAP) { atomicAdd(&(bar)[XB_TMO], 1u); break; } } } } while (0)
; __device__ __forceinline__ void xcd_barrier(const XcdBarrier& b, const int wid) {
;     ...
;         const unsigned old = xb_add(&bar[XB_XSUB(b.x)], 1u);
;         const unsigned gen = old / nloc;
;         if (old + 1u == (gen + 1u) * nloc) {
;             __builtin_amdgcn_fence(__ATOMIC_RELEASE, "agent");
;             asm volatile("s_waitcnt vmcnt(0)" ::: "memory");
;             const unsigned og = xb_add(&bar[XB_TOP], 1u);
;             const unsigned tg = og / nx;
;             if (og + 1u == (tg + 1u) * nx) xb_add(&bar[XB_TOPGEN], 1u);
;             else XB_SPIN(xb_ld(&bar[XB_TOPGEN]) == tg, bar);
;             __builtin_amdgcn_fence(__ATOMIC_ACQUIRE, "agent");
;             xb_add(&bar[XB_XGEN(b.x)], 1u);
;             asm volatile("s_waitcnt vmcnt(0)" ::: "memory");
;         } else {
;             XB_SPIN(xb_ld(&bar[XB_XGEN(b.x)]) == gen, bar);
.LBB0_2567:
	s_or_b64 exec, exec, s[10:11]
	v_cvt_f32_u32_e32 v4, v2
	s_waitcnt vmcnt(0)
	v_readfirstlane_b32 s8, v3
	v_sub_u32_e32 v3, 0, v2
	v_rcp_iflag_f32_e32 v4, v4
	v_add_u32_e32 v5, s8, v1
	v_mul_f32_e32 v4, 0x4f7ffffe, v4
	v_cvt_u32_f32_e32 v4, v4
	v_mul_lo_u32 v1, v3, v4
	v_mul_hi_u32 v1, v4, v1
	v_add_u32_e32 v1, v4, v1
	v_mul_hi_u32 v1, v5, v1
	v_mul_lo_u32 v3, v1, v2
	v_sub_u32_e32 v3, v5, v3
	v_add_u32_e32 v4, 1, v1
	v_cmp_ge_u32_e32 vcc, v3, v2
	s_nop 1
	v_cndmask_b32_e32 v1, v1, v4, vcc
	v_sub_u32_e32 v4, v3, v2
	v_cndmask_b32_e32 v3, v3, v4, vcc
	v_add_u32_e32 v4, 1, v1
	v_cmp_ge_u32_e32 vcc, v3, v2
	v_add_u32_e32 v3, 1, v5
	s_nop 0
	v_cndmask_b32_e32 v1, v1, v4, vcc
	v_mul_lo_u32 v4, v2, v1
	v_add_u32_e32 v2, v4, v2
	v_cmp_ne_u32_e32 vcc, v3, v2
	s_and_saveexec_b64 s[8:9], vcc
	s_xor_b64 s[8:9], exec, s[8:9]
	s_cbranch_execz .LBB0_2581
	s_waitcnt lgkmcnt(0)
	v_mov_b32_e32 v0, 0x7000
	global_load_dword v0, v0, s[46:47] offset:1280 sc1
	s_add_u32 s14, s46, 0x7500
	s_addc_u32 s15, s47, 0
	s_waitcnt vmcnt(0)
	v_cmp_eq_u32_e32 vcc, v0, v1
	s_and_saveexec_b64 s[10:11], vcc
	s_cbranch_execz .LBB0_2580
	s_add_u32 s12, s46, 0x4200
	s_addc_u32 s13, s47, 0
	s_mov_b32 s26, 1
	s_mov_b64 s[16:17], 0
	v_mov_b32_e32 v0, 0
	s_branch .LBB0_2571
